# LRU unit staging: halo-tile row loads and gate-weight loads issued together, one wait (was one round trip per 16-byte piece)
# speedup vs baseline: 1.0064x; 1.0015x over previous
.LBB0_729:
	s_or_b64 exec, exec, s[6:7]
	s_and_b64 vcc, exec, s[4:5]
	v_add_u32_e32 v24, 0x200, v22
	s_cbranch_vccz .Lstg_nowt
	s_lshl_b32 s0, s17, 15
	v_readlane_b32 s1, v254, 30
	s_or_b32 s0, s0, s1
	s_add_u32 s0, s2, s0
	s_addc_u32 s1, s3, 0
	v_lshl_add_u64 v[2:3], s[0:1], 0, v[0:1]
	s_mov_b64 s[0:1], 0x55c4100
	v_ashrrev_i32_e32 v8, 3, v22
	v_lshl_add_u64 v[6:7], v[2:3], 0, s[0:1]
	v_lshlrev_b32_e32 v2, 6, v8
	v_ashrrev_i32_e32 v3, 31, v2
	v_lshl_add_u64 v[2:3], v[2:3], 1, v[6:7]
	global_load_dwordx4 v[152:155], v[2:3], off
	v_add_u32_e32 v0, s52, v0
	v_mad_u64_u32 v[168:169], s[0:1], v8, s92, v[0:1]
	v_ashrrev_i32_e32 v8, 3, v24
	v_lshlrev_b32_e32 v2, 6, v8
	v_ashrrev_i32_e32 v3, 31, v2
	v_lshl_add_u64 v[2:3], v[2:3], 1, v[6:7]
	global_load_dwordx4 v[156:159], v[2:3], off
	v_mad_u64_u32 v[170:171], s[0:1], v8, s92, v[0:1]
	v_add_u32_e32 v2, 0x400, v22
	v_ashrrev_i32_e32 v8, 3, v2
	v_lshlrev_b32_e32 v2, 6, v8
	v_ashrrev_i32_e32 v3, 31, v2
	v_lshl_add_u64 v[2:3], v[2:3], 1, v[6:7]
	global_load_dwordx4 v[160:163], v[2:3], off
	v_mad_u64_u32 v[172:173], s[0:1], v8, s92, v[0:1]
	v_add_u32_e32 v2, 0x600, v22
	v_ashrrev_i32_e32 v8, 3, v2
	v_lshlrev_b32_e32 v2, 6, v8
	v_ashrrev_i32_e32 v3, 31, v2
	v_lshl_add_u64 v[2:3], v[2:3], 1, v[6:7]
	global_load_dwordx4 v[164:167], v[2:3], off
	v_mad_u64_u32 v[6:7], s[0:1], v8, s92, v[0:1]
.Lstg_nowt:
	s_waitcnt vmcnt(0)
	ds_write_b128 v216, v[192:195]
	ds_write_b128 v216, v[196:199] offset:9216
	ds_write_b128 v216, v[200:203] offset:18432
	ds_write_b128 v216, v[204:207] offset:27648
	v_cmp_gt_i32_e32 vcc, 32, v22
	s_and_saveexec_b64 s[10:11], vcc
	ds_write_b128 v216, v[208:211] offset:36864
	s_or_b64 exec, exec, s[10:11]
	s_and_b64 vcc, exec, s[4:5]
	s_cbranch_vccz .LBB0_731
	ds_write_b128 v168, v[152:155]
	ds_write_b128 v170, v[156:159]
	ds_write_b128 v172, v[160:163]
	ds_write_b128 v6, v[164:167]
